# grid barriers: L1 invalidate issued at arrival (overlaps the wait) instead of after the release; XCC leader invalidates with its L2 write-back
# speedup vs baseline: 1.0102x; 1.0081x over previous
; __device__ __forceinline__ unsigned xb_ld(unsigned* p)              { return __hip_atomic_load(p, __ATOMIC_RELAXED, __HIP_MEMORY_SCOPE_AGENT); }
; __device__ __forceinline__ unsigned xb_add(unsigned* p, unsigned v) { return __hip_atomic_fetch_add(p, v, __ATOMIC_RELAXED, __HIP_MEMORY_SCOPE_AGENT); }
; #define XB_SPIN(cond, bar) do { unsigned _sp = 0; while (cond) { __builtin_amdgcn_s_sleep(1); \
;     if ((++_sp & 255u) == 0u) { if (xb_ld(&(bar)[XB_TMO])) break; if (_sp > XB_SPIN_CAP) { atomicAdd(&(bar)[XB_TMO], 1u); break; } } } } while (0)
; __device__ __forceinline__ void xcd_barrier(const XcdBarrier& b) {
;     ...
;         unsigned nloc = b.st[0], nx = b.st[1];
;         if (nloc == 0u) { xcd_barrier_complete(bar, b.x, nloc, nx); b.st[0] = nloc; b.st[1] = nx; }
;         const unsigned old = xb_add(&bar[XB_XSUB(b.x)], 1u);
;         const unsigned gen = old / nloc;
;         if (old + 1u == (gen + 1u) * nloc) {
;             __builtin_amdgcn_fence(__ATOMIC_RELEASE, "agent");
;             asm volatile("s_waitcnt vmcnt(0)" ::: "memory");
;             const unsigned og = xb_add(&bar[XB_TOP], 1u);
;             const unsigned tg = og / nx;
;             if (og + 1u == (tg + 1u) * nx) xb_add(&bar[XB_TOPGEN], 1u);
;             else XB_SPIN(xb_ld(&bar[XB_TOPGEN]) == tg, bar);
;             __builtin_amdgcn_fence(__ATOMIC_ACQUIRE, "agent");
;             xb_add(&bar[XB_XGEN(b.x)], 1u);
;             asm volatile("s_waitcnt vmcnt(0)" ::: "memory");
;         } else {
;             XB_SPIN(xb_ld(&bar[XB_XGEN(b.x)]) == gen, bar);
;             __builtin_amdgcn_fence(__ATOMIC_ACQUIRE, "agent");
.LBB0_123:
	s_or_b64 exec, exec, s[8:9]
	v_cvt_f32_u32_e32 v4, v2
	s_waitcnt vmcnt(0)
	v_readfirstlane_b32 s6, v3
	v_sub_u32_e32 v3, 0, v2
	v_rcp_iflag_f32_e32 v4, v4
	v_add_u32_e32 v5, s6, v1
	v_mul_f32_e32 v4, 0x4f7ffffe, v4
	v_cvt_u32_f32_e32 v4, v4
	v_mul_lo_u32 v1, v3, v4
	v_mul_hi_u32 v1, v4, v1
	v_add_u32_e32 v1, v4, v1
	v_mul_hi_u32 v1, v5, v1
	v_mul_lo_u32 v3, v1, v2
	v_sub_u32_e32 v3, v5, v3
	v_add_u32_e32 v4, 1, v1
	v_cmp_ge_u32_e32 vcc, v3, v2
	s_nop 1
	v_cndmask_b32_e32 v1, v1, v4, vcc
	v_sub_u32_e32 v4, v3, v2
	v_cndmask_b32_e32 v3, v3, v4, vcc
	v_add_u32_e32 v4, 1, v1
	v_cmp_ge_u32_e32 vcc, v3, v2
	v_add_u32_e32 v3, 1, v5
	s_nop 0
	v_cndmask_b32_e32 v1, v1, v4, vcc
	v_mul_lo_u32 v4, v2, v1
	v_add_u32_e32 v2, v4, v2
	v_cmp_ne_u32_e32 vcc, v3, v2
	s_and_saveexec_b64 s[6:7], vcc
	s_xor_b64 s[6:7], exec, s[6:7]
	s_cbranch_execz .LBB0_137
	s_waitcnt lgkmcnt(0)
	buffer_inv sc1
	v_mov_b32_e32 v0, 0x2000
	global_load_dword v0, v0, s[4:5] offset:1024 sc1
	s_add_u32 s12, s4, 0x2400
	s_addc_u32 s13, s5, 0
	s_waitcnt vmcnt(0)
	v_cmp_eq_u32_e32 vcc, v0, v1
	s_and_saveexec_b64 s[8:9], vcc
	s_cbranch_execz .LBB0_136
	s_add_u32 s10, s58, 0xc0200
	s_addc_u32 s11, s59, 0
	s_mov_b32 s24, 1
	s_mov_b64 s[14:15], 0
	v_mov_b32_e32 v0, 0
	s_branch .LBB0_127

; __device__ __forceinline__ unsigned xb_ld(unsigned* p)              { return __hip_atomic_load(p, __ATOMIC_RELAXED, __HIP_MEMORY_SCOPE_AGENT); }
; __device__ __forceinline__ unsigned xb_add(unsigned* p, unsigned v) { return __hip_atomic_fetch_add(p, v, __ATOMIC_RELAXED, __HIP_MEMORY_SCOPE_AGENT); }
; #define XB_SPIN(cond, bar) do { unsigned _sp = 0; while (cond) { __builtin_amdgcn_s_sleep(1); \
;     if ((++_sp & 255u) == 0u) { if (xb_ld(&(bar)[XB_TMO])) break; if (_sp > XB_SPIN_CAP) { atomicAdd(&(bar)[XB_TMO], 1u); break; } } } } while (0)
; __device__ __forceinline__ void xcd_barrier(const XcdBarrier& b) {
;     ...
;         if (old + 1u == (gen + 1u) * nloc) {
;             __builtin_amdgcn_fence(__ATOMIC_RELEASE, "agent");
;             asm volatile("s_waitcnt vmcnt(0)" ::: "memory");
;             const unsigned og = xb_add(&bar[XB_TOP], 1u);
;             const unsigned tg = og / nx;
;             if (og + 1u == (tg + 1u) * nx) xb_add(&bar[XB_TOPGEN], 1u);
;             else XB_SPIN(xb_ld(&bar[XB_TOPGEN]) == tg, bar);
;             __builtin_amdgcn_fence(__ATOMIC_ACQUIRE, "agent");
;             xb_add(&bar[XB_XGEN(b.x)], 1u);
;             asm volatile("s_waitcnt vmcnt(0)" ::: "memory");
;         } else {
;             XB_SPIN(xb_ld(&bar[XB_XGEN(b.x)]) == gen, bar);
;             __builtin_amdgcn_fence(__ATOMIC_ACQUIRE, "agent");
;             asm volatile("s_waitcnt vmcnt(0)" ::: "memory");
.LBB0_136:
	s_or_b64 exec, exec, s[8:9]
	s_waitcnt vmcnt(0)
	s_waitcnt vmcnt(0)
.LBB0_137:
	s_andn2_saveexec_b64 s[6:7], s[6:7]
	s_cbranch_execz .LBB0_157
	s_mov_b64 s[6:7], exec
	buffer_inv sc1
	buffer_wbl2 sc1
	s_waitcnt lgkmcnt(0)
	s_waitcnt vmcnt(0)
	v_mbcnt_lo_u32_b32 v1, s6, 0
	v_mbcnt_hi_u32_b32 v1, s7, v1
	v_cmp_eq_u32_e32 vcc, 0, v1
	s_and_saveexec_b64 s[8:9], vcc
	s_cbranch_execz .LBB0_140
	s_bcnt1_i32_b64 s6, s[6:7]
	v_mov_b32_e32 v2, 0xc3000
	v_mov_b32_e32 v3, s6
	global_atomic_add v2, v2, v3, s[58:59] offset:1024 sc0

; __device__ __forceinline__ unsigned xb_ld(unsigned* p)              { return __hip_atomic_load(p, __ATOMIC_RELAXED, __HIP_MEMORY_SCOPE_AGENT); }
; __device__ __forceinline__ unsigned xb_add(unsigned* p, unsigned v) { return __hip_atomic_fetch_add(p, v, __ATOMIC_RELAXED, __HIP_MEMORY_SCOPE_AGENT); }
; #define XB_SPIN(cond, bar) do { unsigned _sp = 0; while (cond) { __builtin_amdgcn_s_sleep(1); \
;     if ((++_sp & 255u) == 0u) { if (xb_ld(&(bar)[XB_TMO])) break; if (_sp > XB_SPIN_CAP) { atomicAdd(&(bar)[XB_TMO], 1u); break; } } } } while (0)
; __device__ __forceinline__ void xcd_barrier(const XcdBarrier& b) {
;     ...
;             const unsigned og = xb_add(&bar[XB_TOP], 1u);
;             const unsigned tg = og / nx;
;             if (og + 1u == (tg + 1u) * nx) xb_add(&bar[XB_TOPGEN], 1u);
;             else XB_SPIN(xb_ld(&bar[XB_TOPGEN]) == tg, bar);
;             __builtin_amdgcn_fence(__ATOMIC_ACQUIRE, "agent");
;             xb_add(&bar[XB_XGEN(b.x)], 1u);
;             asm volatile("s_waitcnt vmcnt(0)" ::: "memory");
.LBB0_154:
	s_or_b64 exec, exec, s[6:7]
	s_mov_b64 s[6:7], exec
	v_mbcnt_lo_u32_b32 v0, s6, 0
	v_mbcnt_hi_u32_b32 v0, s7, v0
	v_cmp_eq_u32_e32 vcc, 0, v0
	s_and_saveexec_b64 s[8:9], vcc
	s_cbranch_execz .LBB0_156
	s_bcnt1_i32_b64 s6, s[6:7]
	v_mov_b32_e32 v0, 0x2000
	v_mov_b32_e32 v1, s6
	global_atomic_add v0, v1, s[4:5] offset:1024

; __device__ __forceinline__ unsigned xb_ld(unsigned* p)              { return __hip_atomic_load(p, __ATOMIC_RELAXED, __HIP_MEMORY_SCOPE_AGENT); }
; __device__ __forceinline__ unsigned xb_add(unsigned* p, unsigned v) { return __hip_atomic_fetch_add(p, v, __ATOMIC_RELAXED, __HIP_MEMORY_SCOPE_AGENT); }
; #define XB_SPIN(cond, bar) do { unsigned _sp = 0; while (cond) { __builtin_amdgcn_s_sleep(1); \
;     if ((++_sp & 255u) == 0u) { if (xb_ld(&(bar)[XB_TMO])) break; if (_sp > XB_SPIN_CAP) { atomicAdd(&(bar)[XB_TMO], 1u); break; } } } } while (0)
; __device__ __forceinline__ void xcd_barrier(const XcdBarrier& b) {
;     ...
;         unsigned nloc = b.st[0], nx = b.st[1];
;         if (nloc == 0u) { xcd_barrier_complete(bar, b.x, nloc, nx); b.st[0] = nloc; b.st[1] = nx; }
;         const unsigned old = xb_add(&bar[XB_XSUB(b.x)], 1u);
;         const unsigned gen = old / nloc;
;         if (old + 1u == (gen + 1u) * nloc) {
;             __builtin_amdgcn_fence(__ATOMIC_RELEASE, "agent");
;             asm volatile("s_waitcnt vmcnt(0)" ::: "memory");
;             const unsigned og = xb_add(&bar[XB_TOP], 1u);
;             const unsigned tg = og / nx;
;             if (og + 1u == (tg + 1u) * nx) xb_add(&bar[XB_TOPGEN], 1u);
;             else XB_SPIN(xb_ld(&bar[XB_TOPGEN]) == tg, bar);
;             __builtin_amdgcn_fence(__ATOMIC_ACQUIRE, "agent");
;             xb_add(&bar[XB_XGEN(b.x)], 1u);
;             asm volatile("s_waitcnt vmcnt(0)" ::: "memory");
;         } else {
;             XB_SPIN(xb_ld(&bar[XB_XGEN(b.x)]) == gen, bar);
;             __builtin_amdgcn_fence(__ATOMIC_ACQUIRE, "agent");
.LBB0_211:
	s_or_b64 exec, exec, s[12:13]
	v_cvt_f32_u32_e32 v4, v2
	s_waitcnt vmcnt(0)
	v_readfirstlane_b32 s10, v3
	v_sub_u32_e32 v3, 0, v2
	v_rcp_iflag_f32_e32 v4, v4
	v_add_u32_e32 v5, s10, v1
	v_mul_f32_e32 v4, 0x4f7ffffe, v4
	v_cvt_u32_f32_e32 v4, v4
	v_mul_lo_u32 v1, v3, v4
	v_mul_hi_u32 v1, v4, v1
	v_add_u32_e32 v1, v4, v1
	v_mul_hi_u32 v1, v5, v1
	v_mul_lo_u32 v3, v1, v2
	v_sub_u32_e32 v3, v5, v3
	v_add_u32_e32 v4, 1, v1
	v_cmp_ge_u32_e32 vcc, v3, v2
	s_nop 1
	v_cndmask_b32_e32 v1, v1, v4, vcc
	v_sub_u32_e32 v4, v3, v2
	v_cndmask_b32_e32 v3, v3, v4, vcc
	v_add_u32_e32 v4, 1, v1
	v_cmp_ge_u32_e32 vcc, v3, v2
	v_add_u32_e32 v3, 1, v5
	s_nop 0
	v_cndmask_b32_e32 v1, v1, v4, vcc
	v_mul_lo_u32 v4, v2, v1
	v_add_u32_e32 v2, v4, v2
	v_cmp_ne_u32_e32 vcc, v3, v2
	s_and_saveexec_b64 s[10:11], vcc
	s_xor_b64 s[10:11], exec, s[10:11]
	s_cbranch_execz .LBB0_225
	s_waitcnt lgkmcnt(0)
	buffer_inv sc1
	v_mov_b32_e32 v0, 0x2000
	global_load_dword v0, v0, s[8:9] offset:1024 sc1
	s_add_u32 s16, s8, 0x2400
	s_addc_u32 s17, s9, 0
	s_waitcnt vmcnt(0)
	v_cmp_eq_u32_e32 vcc, v0, v1
	s_and_saveexec_b64 s[12:13], vcc
	s_cbranch_execz .LBB0_224
	s_add_u32 s14, s58, 0xc0200
	s_addc_u32 s15, s59, 0
	s_mov_b32 s28, 1
	s_mov_b64 s[18:19], 0
	v_mov_b32_e32 v0, 0
	s_branch .LBB0_215

; __device__ __forceinline__ unsigned xb_ld(unsigned* p)              { return __hip_atomic_load(p, __ATOMIC_RELAXED, __HIP_MEMORY_SCOPE_AGENT); }
; __device__ __forceinline__ unsigned xb_add(unsigned* p, unsigned v) { return __hip_atomic_fetch_add(p, v, __ATOMIC_RELAXED, __HIP_MEMORY_SCOPE_AGENT); }
; #define XB_SPIN(cond, bar) do { unsigned _sp = 0; while (cond) { __builtin_amdgcn_s_sleep(1); \
;     if ((++_sp & 255u) == 0u) { if (xb_ld(&(bar)[XB_TMO])) break; if (_sp > XB_SPIN_CAP) { atomicAdd(&(bar)[XB_TMO], 1u); break; } } } } while (0)
; __device__ __forceinline__ void xcd_barrier(const XcdBarrier& b) {
;     ...
;         if (old + 1u == (gen + 1u) * nloc) {
;             __builtin_amdgcn_fence(__ATOMIC_RELEASE, "agent");
;             asm volatile("s_waitcnt vmcnt(0)" ::: "memory");
;             const unsigned og = xb_add(&bar[XB_TOP], 1u);
;             const unsigned tg = og / nx;
;             if (og + 1u == (tg + 1u) * nx) xb_add(&bar[XB_TOPGEN], 1u);
;             else XB_SPIN(xb_ld(&bar[XB_TOPGEN]) == tg, bar);
;             __builtin_amdgcn_fence(__ATOMIC_ACQUIRE, "agent");
;             xb_add(&bar[XB_XGEN(b.x)], 1u);
;             asm volatile("s_waitcnt vmcnt(0)" ::: "memory");
;         } else {
;             XB_SPIN(xb_ld(&bar[XB_XGEN(b.x)]) == gen, bar);
;             __builtin_amdgcn_fence(__ATOMIC_ACQUIRE, "agent");
;             asm volatile("s_waitcnt vmcnt(0)" ::: "memory");
.LBB0_224:
	s_or_b64 exec, exec, s[12:13]
	s_waitcnt vmcnt(0)
	s_waitcnt vmcnt(0)
.LBB0_225:
	s_andn2_saveexec_b64 s[10:11], s[10:11]
	s_cbranch_execz .LBB0_245
	s_mov_b64 s[10:11], exec
	buffer_inv sc1
	buffer_wbl2 sc1
	s_waitcnt lgkmcnt(0)
	s_waitcnt vmcnt(0)
	v_mbcnt_lo_u32_b32 v1, s10, 0
	v_mbcnt_hi_u32_b32 v1, s11, v1
	v_cmp_eq_u32_e32 vcc, 0, v1
	s_and_saveexec_b64 s[12:13], vcc
	s_cbranch_execz .LBB0_228
	s_bcnt1_i32_b64 s10, s[10:11]
	v_mov_b32_e32 v2, 0xc3000
	v_mov_b32_e32 v3, s10
	global_atomic_add v2, v2, v3, s[58:59] offset:1024 sc0

; __device__ __forceinline__ unsigned xb_ld(unsigned* p)              { return __hip_atomic_load(p, __ATOMIC_RELAXED, __HIP_MEMORY_SCOPE_AGENT); }
; __device__ __forceinline__ unsigned xb_add(unsigned* p, unsigned v) { return __hip_atomic_fetch_add(p, v, __ATOMIC_RELAXED, __HIP_MEMORY_SCOPE_AGENT); }
; #define XB_SPIN(cond, bar) do { unsigned _sp = 0; while (cond) { __builtin_amdgcn_s_sleep(1); \
;     if ((++_sp & 255u) == 0u) { if (xb_ld(&(bar)[XB_TMO])) break; if (_sp > XB_SPIN_CAP) { atomicAdd(&(bar)[XB_TMO], 1u); break; } } } } while (0)
; __device__ __forceinline__ void xcd_barrier(const XcdBarrier& b) {
;     ...
;             const unsigned og = xb_add(&bar[XB_TOP], 1u);
;             const unsigned tg = og / nx;
;             if (og + 1u == (tg + 1u) * nx) xb_add(&bar[XB_TOPGEN], 1u);
;             else XB_SPIN(xb_ld(&bar[XB_TOPGEN]) == tg, bar);
;             __builtin_amdgcn_fence(__ATOMIC_ACQUIRE, "agent");
;             xb_add(&bar[XB_XGEN(b.x)], 1u);
;             asm volatile("s_waitcnt vmcnt(0)" ::: "memory");
.LBB0_242:
	s_or_b64 exec, exec, s[10:11]
	s_mov_b64 s[10:11], exec
	v_mbcnt_lo_u32_b32 v0, s10, 0
	v_mbcnt_hi_u32_b32 v0, s11, v0
	v_cmp_eq_u32_e32 vcc, 0, v0
	s_and_saveexec_b64 s[12:13], vcc
	s_cbranch_execz .LBB0_244
	s_bcnt1_i32_b64 s10, s[10:11]
	v_mov_b32_e32 v0, 0x2000
	v_mov_b32_e32 v1, s10
	global_atomic_add v0, v1, s[8:9] offset:1024

; __device__ __forceinline__ unsigned xb_ld(unsigned* p)              { return __hip_atomic_load(p, __ATOMIC_RELAXED, __HIP_MEMORY_SCOPE_AGENT); }
; __device__ __forceinline__ unsigned xb_add(unsigned* p, unsigned v) { return __hip_atomic_fetch_add(p, v, __ATOMIC_RELAXED, __HIP_MEMORY_SCOPE_AGENT); }
; #define XB_SPIN(cond, bar) do { unsigned _sp = 0; while (cond) { __builtin_amdgcn_s_sleep(1); \
;     if ((++_sp & 255u) == 0u) { if (xb_ld(&(bar)[XB_TMO])) break; if (_sp > XB_SPIN_CAP) { atomicAdd(&(bar)[XB_TMO], 1u); break; } } } } while (0)
; __device__ __forceinline__ void xcd_barrier(const XcdBarrier& b) {
;     ...
;         unsigned nloc = b.st[0], nx = b.st[1];
;         if (nloc == 0u) { xcd_barrier_complete(bar, b.x, nloc, nx); b.st[0] = nloc; b.st[1] = nx; }
;         const unsigned old = xb_add(&bar[XB_XSUB(b.x)], 1u);
;         const unsigned gen = old / nloc;
;         if (old + 1u == (gen + 1u) * nloc) {
;             __builtin_amdgcn_fence(__ATOMIC_RELEASE, "agent");
;             asm volatile("s_waitcnt vmcnt(0)" ::: "memory");
;             const unsigned og = xb_add(&bar[XB_TOP], 1u);
;             const unsigned tg = og / nx;
;             if (og + 1u == (tg + 1u) * nx) xb_add(&bar[XB_TOPGEN], 1u);
;             else XB_SPIN(xb_ld(&bar[XB_TOPGEN]) == tg, bar);
;             __builtin_amdgcn_fence(__ATOMIC_ACQUIRE, "agent");
;             xb_add(&bar[XB_XGEN(b.x)], 1u);
;             asm volatile("s_waitcnt vmcnt(0)" ::: "memory");
;         } else {
;             XB_SPIN(xb_ld(&bar[XB_XGEN(b.x)]) == gen, bar);
;             __builtin_amdgcn_fence(__ATOMIC_ACQUIRE, "agent");
.LBB0_453:
	s_or_b64 exec, exec, s[12:13]
	v_cvt_f32_u32_e32 v4, v2
	s_waitcnt vmcnt(0)
	v_readfirstlane_b32 s8, v3
	v_sub_u32_e32 v3, 0, v2
	v_rcp_iflag_f32_e32 v4, v4
	v_add_u32_e32 v5, s8, v1
	v_mul_f32_e32 v4, 0x4f7ffffe, v4
	v_cvt_u32_f32_e32 v4, v4
	v_mul_lo_u32 v1, v3, v4
	v_mul_hi_u32 v1, v4, v1
	v_add_u32_e32 v1, v4, v1
	v_mul_hi_u32 v1, v5, v1
	v_mul_lo_u32 v3, v1, v2
	v_sub_u32_e32 v3, v5, v3
	v_add_u32_e32 v4, 1, v1
	v_cmp_ge_u32_e32 vcc, v3, v2
	s_nop 1
	v_cndmask_b32_e32 v1, v1, v4, vcc
	v_sub_u32_e32 v4, v3, v2
	v_cndmask_b32_e32 v3, v3, v4, vcc
	v_add_u32_e32 v4, 1, v1
	v_cmp_ge_u32_e32 vcc, v3, v2
	v_add_u32_e32 v3, 1, v5
	s_nop 0
	v_cndmask_b32_e32 v1, v1, v4, vcc
	v_mul_lo_u32 v4, v2, v1
	v_add_u32_e32 v2, v4, v2
	v_cmp_ne_u32_e32 vcc, v3, v2
	s_and_saveexec_b64 s[8:9], vcc
	s_xor_b64 s[8:9], exec, s[8:9]
	s_cbranch_execz .LBB0_467
	s_waitcnt lgkmcnt(0)
	buffer_inv sc1
	v_mov_b32_e32 v0, 0x2000
	global_load_dword v0, v0, s[6:7] offset:1024 sc1
	s_add_u32 s16, s6, 0x2400
	s_addc_u32 s17, s7, 0
	s_waitcnt vmcnt(0)
	v_cmp_eq_u32_e32 vcc, v0, v1
	s_and_saveexec_b64 s[12:13], vcc
	s_cbranch_execz .LBB0_466
	s_add_u32 s14, s58, 0xc0200
	s_addc_u32 s15, s59, 0
	s_mov_b32 s28, 1
	s_mov_b64 s[18:19], 0
	v_mov_b32_e32 v0, 0
	s_branch .LBB0_457

; __device__ __forceinline__ unsigned xb_add(unsigned* p, unsigned v) { return __hip_atomic_fetch_add(p, v, __ATOMIC_RELAXED, __HIP_MEMORY_SCOPE_AGENT); }
; __device__ __forceinline__ void xcd_barrier(const XcdBarrier& b) {
;     ...
;         if (old + 1u == (gen + 1u) * nloc) {
;             __builtin_amdgcn_fence(__ATOMIC_RELEASE, "agent");
;             asm volatile("s_waitcnt vmcnt(0)" ::: "memory");
;             const unsigned og = xb_add(&bar[XB_TOP], 1u);
.LBB0_467:
	s_andn2_saveexec_b64 s[8:9], s[8:9]
	s_cbranch_execz .LBB0_487
	s_mov_b64 s[8:9], exec
	buffer_inv sc1
	s_cmp_eq_u32 s101, 1
	s_cbranch_scc1 .LBB0_484
	buffer_wbl2 sc1
	s_waitcnt lgkmcnt(0)
	s_waitcnt vmcnt(0)
	v_mbcnt_lo_u32_b32 v1, s8, 0
	v_mbcnt_hi_u32_b32 v1, s9, v1
	v_cmp_eq_u32_e32 vcc, 0, v1
	s_and_saveexec_b64 s[12:13], vcc
	s_cbranch_execz .LBB0_470
	s_bcnt1_i32_b64 s8, s[8:9]
	v_mov_b32_e32 v2, 0xc3000
	v_mov_b32_e32 v3, s8
	global_atomic_add v2, v2, v3, s[58:59] offset:1024 sc0

; __device__ __forceinline__ unsigned xb_ld(unsigned* p)              { return __hip_atomic_load(p, __ATOMIC_RELAXED, __HIP_MEMORY_SCOPE_AGENT); }
; __device__ __forceinline__ unsigned xb_add(unsigned* p, unsigned v) { return __hip_atomic_fetch_add(p, v, __ATOMIC_RELAXED, __HIP_MEMORY_SCOPE_AGENT); }
; #define XB_SPIN(cond, bar) do { unsigned _sp = 0; while (cond) { __builtin_amdgcn_s_sleep(1); \
;     if ((++_sp & 255u) == 0u) { if (xb_ld(&(bar)[XB_TMO])) break; if (_sp > XB_SPIN_CAP) { atomicAdd(&(bar)[XB_TMO], 1u); break; } } } } while (0)
; __device__ __forceinline__ void xcd_barrier(const XcdBarrier& b) {
;     ...
;             const unsigned og = xb_add(&bar[XB_TOP], 1u);
;             const unsigned tg = og / nx;
;             if (og + 1u == (tg + 1u) * nx) xb_add(&bar[XB_TOPGEN], 1u);
;             else XB_SPIN(xb_ld(&bar[XB_TOPGEN]) == tg, bar);
;             __builtin_amdgcn_fence(__ATOMIC_ACQUIRE, "agent");
;             xb_add(&bar[XB_XGEN(b.x)], 1u);
;             asm volatile("s_waitcnt vmcnt(0)" ::: "memory");
.LBB0_484:
	s_or_b64 exec, exec, s[8:9]
	s_mov_b64 s[8:9], exec
	v_mbcnt_lo_u32_b32 v0, s8, 0
	v_mbcnt_hi_u32_b32 v0, s9, v0
	v_cmp_eq_u32_e32 vcc, 0, v0
	s_and_saveexec_b64 s[12:13], vcc
	s_cbranch_execz .LBB0_486
	s_bcnt1_i32_b64 s8, s[8:9]
	v_mov_b32_e32 v0, 0x2000
	v_mov_b32_e32 v1, s8
	global_atomic_add v0, v1, s[6:7] offset:1024

; __device__ __forceinline__ unsigned xb_ld(unsigned* p)              { return __hip_atomic_load(p, __ATOMIC_RELAXED, __HIP_MEMORY_SCOPE_AGENT); }
; __device__ __forceinline__ unsigned xb_add(unsigned* p, unsigned v) { return __hip_atomic_fetch_add(p, v, __ATOMIC_RELAXED, __HIP_MEMORY_SCOPE_AGENT); }
; #define XB_SPIN(cond, bar) do { unsigned _sp = 0; while (cond) { __builtin_amdgcn_s_sleep(1); \
;     if ((++_sp & 255u) == 0u) { if (xb_ld(&(bar)[XB_TMO])) break; if (_sp > XB_SPIN_CAP) { atomicAdd(&(bar)[XB_TMO], 1u); break; } } } } while (0)
; __device__ __forceinline__ void xcd_barrier(const XcdBarrier& b) {
;     ...
;         unsigned nloc = b.st[0], nx = b.st[1];
;         if (nloc == 0u) { xcd_barrier_complete(bar, b.x, nloc, nx); b.st[0] = nloc; b.st[1] = nx; }
;         const unsigned old = xb_add(&bar[XB_XSUB(b.x)], 1u);
;         const unsigned gen = old / nloc;
;         if (old + 1u == (gen + 1u) * nloc) {
;             __builtin_amdgcn_fence(__ATOMIC_RELEASE, "agent");
;             asm volatile("s_waitcnt vmcnt(0)" ::: "memory");
;             const unsigned og = xb_add(&bar[XB_TOP], 1u);
;             const unsigned tg = og / nx;
;             if (og + 1u == (tg + 1u) * nx) xb_add(&bar[XB_TOPGEN], 1u);
;             else XB_SPIN(xb_ld(&bar[XB_TOPGEN]) == tg, bar);
;             __builtin_amdgcn_fence(__ATOMIC_ACQUIRE, "agent");
;             xb_add(&bar[XB_XGEN(b.x)], 1u);
;             asm volatile("s_waitcnt vmcnt(0)" ::: "memory");
;         } else {
;             XB_SPIN(xb_ld(&bar[XB_XGEN(b.x)]) == gen, bar);
;             __builtin_amdgcn_fence(__ATOMIC_ACQUIRE, "agent");
.LBB0_529:
	s_or_b64 exec, exec, s[10:11]
	v_cvt_f32_u32_e32 v4, v2
	s_waitcnt vmcnt(0)
	v_readfirstlane_b32 s6, v3
	v_sub_u32_e32 v3, 0, v2
	v_rcp_iflag_f32_e32 v4, v4
	v_add_u32_e32 v5, s6, v1
	v_mul_f32_e32 v4, 0x4f7ffffe, v4
	v_cvt_u32_f32_e32 v4, v4
	v_mul_lo_u32 v1, v3, v4
	v_mul_hi_u32 v1, v4, v1
	v_add_u32_e32 v1, v4, v1
	v_mul_hi_u32 v1, v5, v1
	v_mul_lo_u32 v3, v1, v2
	v_sub_u32_e32 v3, v5, v3
	v_add_u32_e32 v4, 1, v1
	v_cmp_ge_u32_e32 vcc, v3, v2
	s_nop 1
	v_cndmask_b32_e32 v1, v1, v4, vcc
	v_sub_u32_e32 v4, v3, v2
	v_cndmask_b32_e32 v3, v3, v4, vcc
	v_add_u32_e32 v4, 1, v1
	v_cmp_ge_u32_e32 vcc, v3, v2
	v_add_u32_e32 v3, 1, v5
	s_nop 0
	v_cndmask_b32_e32 v1, v1, v4, vcc
	v_mul_lo_u32 v4, v2, v1
	v_add_u32_e32 v2, v4, v2
	v_cmp_ne_u32_e32 vcc, v3, v2
	s_and_saveexec_b64 s[6:7], vcc
	s_xor_b64 s[6:7], exec, s[6:7]
	s_cbranch_execz .LBB0_543
	s_waitcnt lgkmcnt(0)
	buffer_inv sc1
	v_mov_b32_e32 v0, 0x2000
	global_load_dword v0, v0, s[4:5] offset:1024 sc1
	s_add_u32 s14, s4, 0x2400
	s_addc_u32 s15, s5, 0
	s_waitcnt vmcnt(0)
	v_cmp_eq_u32_e32 vcc, v0, v1
	s_and_saveexec_b64 s[10:11], vcc
	s_cbranch_execz .LBB0_542
	s_add_u32 s12, s58, 0xc0200
	s_addc_u32 s13, s59, 0
	s_mov_b32 s26, 1
	s_mov_b64 s[16:17], 0
	v_mov_b32_e32 v0, 0
	s_branch .LBB0_533

; __device__ __forceinline__ unsigned xb_ld(unsigned* p)              { return __hip_atomic_load(p, __ATOMIC_RELAXED, __HIP_MEMORY_SCOPE_AGENT); }
; __device__ __forceinline__ unsigned xb_add(unsigned* p, unsigned v) { return __hip_atomic_fetch_add(p, v, __ATOMIC_RELAXED, __HIP_MEMORY_SCOPE_AGENT); }
; #define XB_SPIN(cond, bar) do { unsigned _sp = 0; while (cond) { __builtin_amdgcn_s_sleep(1); \
;     if ((++_sp & 255u) == 0u) { if (xb_ld(&(bar)[XB_TMO])) break; if (_sp > XB_SPIN_CAP) { atomicAdd(&(bar)[XB_TMO], 1u); break; } } } } while (0)
; __device__ __forceinline__ void xcd_barrier(const XcdBarrier& b) {
;     ...
;         if (old + 1u == (gen + 1u) * nloc) {
;             __builtin_amdgcn_fence(__ATOMIC_RELEASE, "agent");
;             asm volatile("s_waitcnt vmcnt(0)" ::: "memory");
;             const unsigned og = xb_add(&bar[XB_TOP], 1u);
;             const unsigned tg = og / nx;
;             if (og + 1u == (tg + 1u) * nx) xb_add(&bar[XB_TOPGEN], 1u);
;             else XB_SPIN(xb_ld(&bar[XB_TOPGEN]) == tg, bar);
;             __builtin_amdgcn_fence(__ATOMIC_ACQUIRE, "agent");
;             xb_add(&bar[XB_XGEN(b.x)], 1u);
;             asm volatile("s_waitcnt vmcnt(0)" ::: "memory");
;         } else {
;             XB_SPIN(xb_ld(&bar[XB_XGEN(b.x)]) == gen, bar);
;             __builtin_amdgcn_fence(__ATOMIC_ACQUIRE, "agent");
;             asm volatile("s_waitcnt vmcnt(0)" ::: "memory");
.LBB0_542:
	s_or_b64 exec, exec, s[10:11]
	s_waitcnt vmcnt(0)
	s_waitcnt vmcnt(0)
.LBB0_543:
	s_andn2_saveexec_b64 s[6:7], s[6:7]
	s_cbranch_execz .LBB0_563
	s_mov_b64 s[6:7], exec
	buffer_inv sc1
	s_cmp_eq_u32 s101, 1
	s_cbranch_scc1 .LBB0_560
	buffer_wbl2 sc1
	s_waitcnt lgkmcnt(0)
	s_waitcnt vmcnt(0)
	v_mbcnt_lo_u32_b32 v1, s6, 0
	v_mbcnt_hi_u32_b32 v1, s7, v1
	v_cmp_eq_u32_e32 vcc, 0, v1
	s_and_saveexec_b64 s[10:11], vcc
	s_cbranch_execz .LBB0_546
	s_bcnt1_i32_b64 s6, s[6:7]
	v_mov_b32_e32 v2, 0xc3000
	v_mov_b32_e32 v3, s6
	global_atomic_add v2, v2, v3, s[58:59] offset:1024 sc0

; __device__ __forceinline__ unsigned xb_ld(unsigned* p)              { return __hip_atomic_load(p, __ATOMIC_RELAXED, __HIP_MEMORY_SCOPE_AGENT); }
; __device__ __forceinline__ unsigned xb_add(unsigned* p, unsigned v) { return __hip_atomic_fetch_add(p, v, __ATOMIC_RELAXED, __HIP_MEMORY_SCOPE_AGENT); }
; #define XB_SPIN(cond, bar) do { unsigned _sp = 0; while (cond) { __builtin_amdgcn_s_sleep(1); \
;     if ((++_sp & 255u) == 0u) { if (xb_ld(&(bar)[XB_TMO])) break; if (_sp > XB_SPIN_CAP) { atomicAdd(&(bar)[XB_TMO], 1u); break; } } } } while (0)
; __device__ __forceinline__ void xcd_barrier(const XcdBarrier& b) {
;     ...
;             const unsigned og = xb_add(&bar[XB_TOP], 1u);
;             const unsigned tg = og / nx;
;             if (og + 1u == (tg + 1u) * nx) xb_add(&bar[XB_TOPGEN], 1u);
;             else XB_SPIN(xb_ld(&bar[XB_TOPGEN]) == tg, bar);
;             __builtin_amdgcn_fence(__ATOMIC_ACQUIRE, "agent");
;             xb_add(&bar[XB_XGEN(b.x)], 1u);
;             asm volatile("s_waitcnt vmcnt(0)" ::: "memory");
.LBB0_560:
	s_or_b64 exec, exec, s[6:7]
	s_mov_b64 s[6:7], exec
	v_mbcnt_lo_u32_b32 v0, s6, 0
	v_mbcnt_hi_u32_b32 v0, s7, v0
	v_cmp_eq_u32_e32 vcc, 0, v0
	s_and_saveexec_b64 s[10:11], vcc
	s_cbranch_execz .LBB0_562
	s_bcnt1_i32_b64 s6, s[6:7]
	v_mov_b32_e32 v0, 0x2000
	v_mov_b32_e32 v1, s6
	global_atomic_add v0, v1, s[4:5] offset:1024

; __device__ __forceinline__ unsigned xb_ld(unsigned* p)              { return __hip_atomic_load(p, __ATOMIC_RELAXED, __HIP_MEMORY_SCOPE_AGENT); }
; __device__ __forceinline__ unsigned xb_add(unsigned* p, unsigned v) { return __hip_atomic_fetch_add(p, v, __ATOMIC_RELAXED, __HIP_MEMORY_SCOPE_AGENT); }
; #define XB_SPIN(cond, bar) do { unsigned _sp = 0; while (cond) { __builtin_amdgcn_s_sleep(1); \
;     if ((++_sp & 255u) == 0u) { if (xb_ld(&(bar)[XB_TMO])) break; if (_sp > XB_SPIN_CAP) { atomicAdd(&(bar)[XB_TMO], 1u); break; } } } } while (0)
; __device__ __forceinline__ void xcd_barrier(const XcdBarrier& b) {
;     ...
;         unsigned nloc = b.st[0], nx = b.st[1];
;         if (nloc == 0u) { xcd_barrier_complete(bar, b.x, nloc, nx); b.st[0] = nloc; b.st[1] = nx; }
;         const unsigned old = xb_add(&bar[XB_XSUB(b.x)], 1u);
;         const unsigned gen = old / nloc;
;         if (old + 1u == (gen + 1u) * nloc) {
;             __builtin_amdgcn_fence(__ATOMIC_RELEASE, "agent");
;             asm volatile("s_waitcnt vmcnt(0)" ::: "memory");
;             const unsigned og = xb_add(&bar[XB_TOP], 1u);
;             const unsigned tg = og / nx;
;             if (og + 1u == (tg + 1u) * nx) xb_add(&bar[XB_TOPGEN], 1u);
;             else XB_SPIN(xb_ld(&bar[XB_TOPGEN]) == tg, bar);
;             __builtin_amdgcn_fence(__ATOMIC_ACQUIRE, "agent");
;             xb_add(&bar[XB_XGEN(b.x)], 1u);
;             asm volatile("s_waitcnt vmcnt(0)" ::: "memory");
;         } else {
;             XB_SPIN(xb_ld(&bar[XB_XGEN(b.x)]) == gen, bar);
;             __builtin_amdgcn_fence(__ATOMIC_ACQUIRE, "agent");
.LBB0_623:
	s_or_b64 exec, exec, s[14:15]
	v_cvt_f32_u32_e32 v4, v2
	s_waitcnt vmcnt(0)
	v_readfirstlane_b32 s12, v3
	v_sub_u32_e32 v3, 0, v2
	v_rcp_iflag_f32_e32 v4, v4
	v_add_u32_e32 v5, s12, v1
	v_mul_f32_e32 v4, 0x4f7ffffe, v4
	v_cvt_u32_f32_e32 v4, v4
	v_mul_lo_u32 v1, v3, v4
	v_mul_hi_u32 v1, v4, v1
	v_add_u32_e32 v1, v4, v1
	v_mul_hi_u32 v1, v5, v1
	v_mul_lo_u32 v3, v1, v2
	v_sub_u32_e32 v3, v5, v3
	v_add_u32_e32 v4, 1, v1
	v_cmp_ge_u32_e32 vcc, v3, v2
	s_nop 1
	v_cndmask_b32_e32 v1, v1, v4, vcc
	v_sub_u32_e32 v4, v3, v2
	v_cndmask_b32_e32 v3, v3, v4, vcc
	v_add_u32_e32 v4, 1, v1
	v_cmp_ge_u32_e32 vcc, v3, v2
	v_add_u32_e32 v3, 1, v5
	s_nop 0
	v_cndmask_b32_e32 v1, v1, v4, vcc
	v_mul_lo_u32 v4, v2, v1
	v_add_u32_e32 v2, v4, v2
	v_cmp_ne_u32_e32 vcc, v3, v2
	s_and_saveexec_b64 s[12:13], vcc
	s_xor_b64 s[12:13], exec, s[12:13]
	s_cbranch_execz .LBB0_637
	s_waitcnt lgkmcnt(0)
	buffer_inv sc1
	v_mov_b32_e32 v0, 0x2000
	global_load_dword v0, v0, s[6:7] offset:1024 sc1
	s_add_u32 s18, s6, 0x2400
	s_addc_u32 s19, s7, 0
	s_waitcnt vmcnt(0)
	v_cmp_eq_u32_e32 vcc, v0, v1
	s_and_saveexec_b64 s[14:15], vcc
	s_cbranch_execz .LBB0_636
	s_add_u32 s16, s58, 0xc0200
	s_addc_u32 s17, s59, 0
	s_mov_b32 s30, 1
	s_mov_b64 s[20:21], 0
	v_mov_b32_e32 v0, 0
	s_branch .LBB0_627

; __device__ __forceinline__ unsigned xb_ld(unsigned* p)              { return __hip_atomic_load(p, __ATOMIC_RELAXED, __HIP_MEMORY_SCOPE_AGENT); }
; __device__ __forceinline__ unsigned xb_add(unsigned* p, unsigned v) { return __hip_atomic_fetch_add(p, v, __ATOMIC_RELAXED, __HIP_MEMORY_SCOPE_AGENT); }
; #define XB_SPIN(cond, bar) do { unsigned _sp = 0; while (cond) { __builtin_amdgcn_s_sleep(1); \
;     if ((++_sp & 255u) == 0u) { if (xb_ld(&(bar)[XB_TMO])) break; if (_sp > XB_SPIN_CAP) { atomicAdd(&(bar)[XB_TMO], 1u); break; } } } } while (0)
; __device__ __forceinline__ void xcd_barrier(const XcdBarrier& b) {
;     ...
;         if (old + 1u == (gen + 1u) * nloc) {
;             __builtin_amdgcn_fence(__ATOMIC_RELEASE, "agent");
;             asm volatile("s_waitcnt vmcnt(0)" ::: "memory");
;             const unsigned og = xb_add(&bar[XB_TOP], 1u);
;             const unsigned tg = og / nx;
;             if (og + 1u == (tg + 1u) * nx) xb_add(&bar[XB_TOPGEN], 1u);
;             else XB_SPIN(xb_ld(&bar[XB_TOPGEN]) == tg, bar);
;             __builtin_amdgcn_fence(__ATOMIC_ACQUIRE, "agent");
;             xb_add(&bar[XB_XGEN(b.x)], 1u);
;             asm volatile("s_waitcnt vmcnt(0)" ::: "memory");
;         } else {
;             XB_SPIN(xb_ld(&bar[XB_XGEN(b.x)]) == gen, bar);
;             __builtin_amdgcn_fence(__ATOMIC_ACQUIRE, "agent");
;             asm volatile("s_waitcnt vmcnt(0)" ::: "memory");
.LBB0_636:
	s_or_b64 exec, exec, s[14:15]
	s_waitcnt vmcnt(0)
	s_waitcnt vmcnt(0)
.LBB0_637:
	s_andn2_saveexec_b64 s[12:13], s[12:13]
	s_cbranch_execz .LBB0_657
	s_mov_b64 s[12:13], exec
	buffer_inv sc1
	buffer_wbl2 sc1
	s_waitcnt lgkmcnt(0)
	s_waitcnt vmcnt(0)
	v_mbcnt_lo_u32_b32 v1, s12, 0
	v_mbcnt_hi_u32_b32 v1, s13, v1
	v_cmp_eq_u32_e32 vcc, 0, v1
	s_and_saveexec_b64 s[14:15], vcc
	s_cbranch_execz .LBB0_640
	s_bcnt1_i32_b64 s12, s[12:13]
	v_mov_b32_e32 v2, 0xc3000
	v_mov_b32_e32 v3, s12
	global_atomic_add v2, v2, v3, s[58:59] offset:1024 sc0

; __device__ __forceinline__ unsigned xb_ld(unsigned* p)              { return __hip_atomic_load(p, __ATOMIC_RELAXED, __HIP_MEMORY_SCOPE_AGENT); }
; __device__ __forceinline__ unsigned xb_add(unsigned* p, unsigned v) { return __hip_atomic_fetch_add(p, v, __ATOMIC_RELAXED, __HIP_MEMORY_SCOPE_AGENT); }
; #define XB_SPIN(cond, bar) do { unsigned _sp = 0; while (cond) { __builtin_amdgcn_s_sleep(1); \
;     if ((++_sp & 255u) == 0u) { if (xb_ld(&(bar)[XB_TMO])) break; if (_sp > XB_SPIN_CAP) { atomicAdd(&(bar)[XB_TMO], 1u); break; } } } } while (0)
; __device__ __forceinline__ void xcd_barrier(const XcdBarrier& b) {
;     ...
;             const unsigned og = xb_add(&bar[XB_TOP], 1u);
;             const unsigned tg = og / nx;
;             if (og + 1u == (tg + 1u) * nx) xb_add(&bar[XB_TOPGEN], 1u);
;             else XB_SPIN(xb_ld(&bar[XB_TOPGEN]) == tg, bar);
;             __builtin_amdgcn_fence(__ATOMIC_ACQUIRE, "agent");
;             xb_add(&bar[XB_XGEN(b.x)], 1u);
;             asm volatile("s_waitcnt vmcnt(0)" ::: "memory");
.LBB0_654:
	s_or_b64 exec, exec, s[12:13]
	s_mov_b64 s[12:13], exec
	v_mbcnt_lo_u32_b32 v0, s12, 0
	v_mbcnt_hi_u32_b32 v0, s13, v0
	v_cmp_eq_u32_e32 vcc, 0, v0
	s_and_saveexec_b64 s[14:15], vcc
	s_cbranch_execz .LBB0_656
	s_bcnt1_i32_b64 s12, s[12:13]
	v_mov_b32_e32 v0, 0x2000
	v_mov_b32_e32 v1, s12
	global_atomic_add v0, v1, s[6:7] offset:1024

; __device__ __forceinline__ unsigned xb_ld(unsigned* p)              { return __hip_atomic_load(p, __ATOMIC_RELAXED, __HIP_MEMORY_SCOPE_AGENT); }
; __device__ __forceinline__ unsigned xb_add(unsigned* p, unsigned v) { return __hip_atomic_fetch_add(p, v, __ATOMIC_RELAXED, __HIP_MEMORY_SCOPE_AGENT); }
; #define XB_SPIN(cond, bar) do { unsigned _sp = 0; while (cond) { __builtin_amdgcn_s_sleep(1); \
;     if ((++_sp & 255u) == 0u) { if (xb_ld(&(bar)[XB_TMO])) break; if (_sp > XB_SPIN_CAP) { atomicAdd(&(bar)[XB_TMO], 1u); break; } } } } while (0)
; __device__ __forceinline__ void xcd_barrier(const XcdBarrier& b) {
;     ...
;         unsigned nloc = b.st[0], nx = b.st[1];
;         if (nloc == 0u) { xcd_barrier_complete(bar, b.x, nloc, nx); b.st[0] = nloc; b.st[1] = nx; }
;         const unsigned old = xb_add(&bar[XB_XSUB(b.x)], 1u);
;         const unsigned gen = old / nloc;
;         if (old + 1u == (gen + 1u) * nloc) {
;             __builtin_amdgcn_fence(__ATOMIC_RELEASE, "agent");
;             asm volatile("s_waitcnt vmcnt(0)" ::: "memory");
;             const unsigned og = xb_add(&bar[XB_TOP], 1u);
;             const unsigned tg = og / nx;
;             if (og + 1u == (tg + 1u) * nx) xb_add(&bar[XB_TOPGEN], 1u);
;             else XB_SPIN(xb_ld(&bar[XB_TOPGEN]) == tg, bar);
;             __builtin_amdgcn_fence(__ATOMIC_ACQUIRE, "agent");
;             xb_add(&bar[XB_XGEN(b.x)], 1u);
;             asm volatile("s_waitcnt vmcnt(0)" ::: "memory");
;         } else {
;             XB_SPIN(xb_ld(&bar[XB_XGEN(b.x)]) == gen, bar);
;             __builtin_amdgcn_fence(__ATOMIC_ACQUIRE, "agent");
.LBB0_691:
	s_or_b64 exec, exec, s[12:13]
	v_cvt_f32_u32_e32 v4, v2
	s_waitcnt vmcnt(0)
	v_readfirstlane_b32 s3, v3
	v_sub_u32_e32 v3, 0, v2
	v_rcp_iflag_f32_e32 v4, v4
	v_add_u32_e32 v5, s3, v1
	v_mul_f32_e32 v4, 0x4f7ffffe, v4
	v_cvt_u32_f32_e32 v4, v4
	v_mul_lo_u32 v1, v3, v4
	v_mul_hi_u32 v1, v4, v1
	v_add_u32_e32 v1, v4, v1
	v_mul_hi_u32 v1, v5, v1
	v_mul_lo_u32 v3, v1, v2
	v_sub_u32_e32 v3, v5, v3
	v_add_u32_e32 v4, 1, v1
	v_cmp_ge_u32_e32 vcc, v3, v2
	s_nop 1
	v_cndmask_b32_e32 v1, v1, v4, vcc
	v_sub_u32_e32 v4, v3, v2
	v_cndmask_b32_e32 v3, v3, v4, vcc
	v_add_u32_e32 v4, 1, v1
	v_cmp_ge_u32_e32 vcc, v3, v2
	v_add_u32_e32 v3, 1, v5
	s_nop 0
	v_cndmask_b32_e32 v1, v1, v4, vcc
	v_mul_lo_u32 v4, v2, v1
	v_add_u32_e32 v2, v4, v2
	v_cmp_ne_u32_e32 vcc, v3, v2
	s_and_saveexec_b64 s[10:11], vcc
	s_xor_b64 s[10:11], exec, s[10:11]
	s_cbranch_execz .LBB0_705
	s_waitcnt lgkmcnt(0)
	buffer_inv sc1
	v_mov_b32_e32 v0, 0x2000
	global_load_dword v0, v0, s[6:7] offset:1024 sc1
	s_add_u32 s16, s6, 0x2400
	s_addc_u32 s17, s7, 0
	s_waitcnt vmcnt(0)
	v_cmp_eq_u32_e32 vcc, v0, v1
	s_and_saveexec_b64 s[12:13], vcc
	s_cbranch_execz .LBB0_704
	s_add_u32 s14, s58, 0xc0200
	s_addc_u32 s15, s59, 0
	s_mov_b32 s3, 1
	s_mov_b64 s[18:19], 0
	v_mov_b32_e32 v0, 0
	s_branch .LBB0_695

; __device__ __forceinline__ unsigned xb_add(unsigned* p, unsigned v) { return __hip_atomic_fetch_add(p, v, __ATOMIC_RELAXED, __HIP_MEMORY_SCOPE_AGENT); }
; __device__ __forceinline__ void xcd_barrier(const XcdBarrier& b) {
;     ...
;         if (old + 1u == (gen + 1u) * nloc) {
;             __builtin_amdgcn_fence(__ATOMIC_RELEASE, "agent");
;             asm volatile("s_waitcnt vmcnt(0)" ::: "memory");
;             const unsigned og = xb_add(&bar[XB_TOP], 1u);
.LBB0_705:
	s_andn2_saveexec_b64 s[10:11], s[10:11]
	s_cbranch_execz .LBB0_725
	s_mov_b64 s[10:11], exec
	buffer_inv sc1
	s_cmp_eq_u32 s101, 1
	s_cbranch_scc1 .LBB0_722
	buffer_wbl2 sc1
	s_waitcnt lgkmcnt(0)
	s_waitcnt vmcnt(0)
	v_mbcnt_lo_u32_b32 v1, s10, 0
	v_mbcnt_hi_u32_b32 v1, s11, v1
	v_cmp_eq_u32_e32 vcc, 0, v1
	s_and_saveexec_b64 s[12:13], vcc
	s_cbranch_execz .LBB0_708
	s_bcnt1_i32_b64 s3, s[10:11]
	v_mov_b32_e32 v2, 0xc3000
	v_mov_b32_e32 v3, s3
	global_atomic_add v2, v2, v3, s[58:59] offset:1024 sc0

; __device__ __forceinline__ unsigned xb_ld(unsigned* p)              { return __hip_atomic_load(p, __ATOMIC_RELAXED, __HIP_MEMORY_SCOPE_AGENT); }
; __device__ __forceinline__ unsigned xb_add(unsigned* p, unsigned v) { return __hip_atomic_fetch_add(p, v, __ATOMIC_RELAXED, __HIP_MEMORY_SCOPE_AGENT); }
; #define XB_SPIN(cond, bar) do { unsigned _sp = 0; while (cond) { __builtin_amdgcn_s_sleep(1); \
;     if ((++_sp & 255u) == 0u) { if (xb_ld(&(bar)[XB_TMO])) break; if (_sp > XB_SPIN_CAP) { atomicAdd(&(bar)[XB_TMO], 1u); break; } } } } while (0)
; __device__ __forceinline__ void xcd_barrier(const XcdBarrier& b) {
;     ...
;             const unsigned og = xb_add(&bar[XB_TOP], 1u);
;             const unsigned tg = og / nx;
;             if (og + 1u == (tg + 1u) * nx) xb_add(&bar[XB_TOPGEN], 1u);
;             else XB_SPIN(xb_ld(&bar[XB_TOPGEN]) == tg, bar);
;             __builtin_amdgcn_fence(__ATOMIC_ACQUIRE, "agent");
;             xb_add(&bar[XB_XGEN(b.x)], 1u);
;             asm volatile("s_waitcnt vmcnt(0)" ::: "memory");
.LBB0_722:
	s_or_b64 exec, exec, s[10:11]
	s_mov_b64 s[10:11], exec
	v_mbcnt_lo_u32_b32 v0, s10, 0
	v_mbcnt_hi_u32_b32 v0, s11, v0
	v_cmp_eq_u32_e32 vcc, 0, v0
	s_and_saveexec_b64 s[12:13], vcc
	s_cbranch_execz .LBB0_724
	s_bcnt1_i32_b64 s3, s[10:11]
	v_mov_b32_e32 v0, 0x2000
	v_mov_b32_e32 v1, s3
	global_atomic_add v0, v1, s[6:7] offset:1024
